# gate/up epilogue: the two cross-lane reduction steps use v_permlane16_swap / v_permlane32_swap (VALU) instead of ds_bpermute LDS round trips (14 of 16 sites)
# baseline (speedup 1.0000x reference)
; #define SCHED __builtin_amdgcn_sched_barrier(0)
; DI float red_fq(float s) { s += __shfl_xor(s, 16); s += __shfl_xor(s, 32); return s; }
; #pragma unroll
;   for (int j = 0; j < 4; ++j) { const int sl = 4 * fq + j; s += (sl >= lo && sl < lo + n) ? v[j] : 0.f; }
;   return red_fq(s); }
; DI float rstd_slots(const float* ssq, int tok, int fq, int lo, int n, float width) {
;   const f32x4 v = *(const f32x4*)(ssq + (size_t)tok * 16 + 4 * fq);
;   return __builtin_amdgcn_rsqf(slots_sum(v, fq, lo, n) / width + EPS);
;   DI void finish(f32x4 (&acc)[2][2][4][2], int tb, int q, int lane) {
;     asm volatile("" : "+v"(lane));
;     const int fr = lane & 15, fq = lane >> 4;
; #pragma unroll
;     for (int ai = 0; ai < 2; ++ai)
; #pragma unroll
;       for (int m = 0; m < 4; ++m) {
;         SCHED;
;         const int tok = tb + ai * 128 + m * 16 + fr;
;         const float rstd = rstd_slots(ssqx, tok, fq, 0, 16, 1024.f);
;         f32x4 a[2];
; #pragma unroll
;         for (int n = 0; n < 2; ++n)
; #pragma unroll
;           for (int j = 0; j < 4; ++j) {
;             const float g = acc[ai][0][m][n][j] * rstd, u = acc[ai][1][m][n][j] * rstd;
;             a[n][j] = g * __builtin_amdgcn_rcpf(1.f + __builtin_amdgcn_exp2f(-g * LOG2E)) * u;
;           }
;         tok_st32(ACT + (size_t)tok * DFF + q * 32, a[0], a[1], fq);
;       }
.LBB0_32:
	s_lshl_b32 s0, s8, 8
	v_mov_b32_e32 v0, v137
	s_add_i32 s0, s0, s31
	v_xor_b32_e32 v132, 32, v183
	v_and_or_b32 v130, v0, 15, s0
	v_ashrrev_i32_e32 v0, 2, v0
	v_and_b32_e32 v134, -4, v0
	v_or_b32_e32 v131, 1, v134
	v_cmp_gt_i32_e64 s[0:1], 16, v131
	v_or_b32_e32 v131, 2, v134
	v_cmp_lt_i32_e64 s[6:7], -1, v0
	v_cmp_gt_i32_e64 s[4:5], 16, v131
	v_or_b32_e32 v0, 3, v0
	v_and_b32_e32 v131, 64, v183
	v_cmp_gt_i32_e32 vcc, 16, v134
	v_cmp_gt_i32_e64 s[8:9], 16, v0
	v_xor_b32_e32 v0, 16, v183
	v_add_u32_e32 v131, 64, v131
	s_and_b64 vcc, s[6:7], vcc
	s_and_b64 s[0:1], s[6:7], s[0:1]
	s_and_b64 s[4:5], s[6:7], s[4:5]
	s_and_b64 s[6:7], s[6:7], s[8:9]
	v_cmp_lt_i32_e64 s[8:9], v0, v131
	v_ashrrev_i32_e32 v135, 31, v134
	s_nop 0
	v_cndmask_b32_e64 v0, v183, v0, s[8:9]
	v_cmp_lt_i32_e64 s[8:9], v132, v131
	v_lshlrev_b32_e32 v0, 2, v0
	s_nop 0
	v_cndmask_b32_e64 v131, v183, v132, s[8:9]
	s_lshl_b32 s8, s38, 7
	s_or_b32 s8, s8, s36
	v_lshlrev_b32_e32 v140, 2, v131
	s_ashr_i32 s9, s8, 31
	v_ashrrev_i32_e32 v131, 31, v130
	v_lshlrev_b64 v[132:133], 6, v[130:131]
	v_lshl_add_u64 v[142:143], s[66:67], 0, v[132:133]
	v_lshlrev_b64 v[132:133], 2, v[134:135]
	v_lshl_add_u64 v[142:143], v[142:143], 0, v[132:133]
	global_load_dwordx4 v[142:145], v[142:143], off
	v_readlane_b32 s38, v249, 51
	v_readlane_b32 s39, v249, 52
	s_lshl_b64 s[8:9], s[8:9], 1
	s_waitcnt vmcnt(0)
	v_add_f32_e32 v131, 0, v142
	v_cndmask_b32_e32 v131, 0, v131, vcc
	v_cndmask_b32_e64 v141, 0, v143, s[0:1]
	v_add_f32_e32 v131, v141, v131
	v_cndmask_b32_e64 v141, 0, v144, s[4:5]
	v_add_f32_e32 v131, v141, v131
	v_cndmask_b32_e64 v141, 0, v145, s[6:7]
	v_add_f32_e32 v131, v141, v131
	v_mov_b32_e32 v141, v131
	s_nop 1
	v_permlane16_swap_b32_e32 v141, v131
	v_add_f32_e32 v131, v131, v141
	v_mov_b32_e32 v141, v131
	s_nop 1
	v_permlane32_swap_b32_e32 v141, v131
	v_add_f32_e32 v131, v131, v141
	v_fmamk_f32 v131, v131, 0x3a800000, v181
	v_rsq_f32_e32 v142, v131
	s_nop 0
	v_pk_mul_f32 v[126:127], v[126:127], v[142:143] op_sel_hi:[1,0]
	s_nop 0
	v_mul_f32_e32 v131, 0xbfb8aa3b, v126
	v_exp_f32_e32 v131, v131
	v_pk_mul_f32 v[118:119], v[118:119], v[142:143] op_sel_hi:[1,0]
	v_pk_mul_f32 v[120:121], v[120:121], v[142:143] op_sel_hi:[1,0]
	v_pk_mul_f32 v[122:123], v[122:123], v[142:143] op_sel_hi:[1,0]
	v_add_f32_e32 v131, 1.0, v131
	v_rcp_f32_e32 v144, v131
	v_mul_f32_e32 v131, 0xbfb8aa3b, v127
	v_exp_f32_e32 v131, v131
	v_pk_mul_f32 v[114:115], v[114:115], v[142:143] op_sel_hi:[1,0]
	v_pk_mul_f32 v[116:117], v[116:117], v[142:143] op_sel_hi:[1,0]
	v_add_f32_e32 v131, 1.0, v131
	v_rcp_f32_e32 v145, v131
	s_nop 0
	v_pk_mul_f32 v[126:127], v[126:127], v[144:145]
	s_nop 0
	v_pk_mul_f32 v[118:119], v[118:119], v[126:127]
	v_pk_mul_f32 v[126:127], v[128:129], v[142:143] op_sel_hi:[1,0]
	v_cvt_pk_bf16_f32 v118, v118, v119
	v_mul_f32_e32 v128, 0xbfb8aa3b, v126
	v_mul_f32_e32 v129, 0xbfb8aa3b, v127
	v_exp_f32_e32 v128, v128
	v_exp_f32_e32 v129, v129
	v_add_f32_e32 v128, 1.0, v128
	v_add_f32_e32 v129, 1.0, v129
	v_rcp_f32_e32 v128, v128
	v_rcp_f32_e32 v129, v129
	s_nop 0
	v_pk_mul_f32 v[126:127], v[126:127], v[128:129]
	s_nop 0
	v_pk_mul_f32 v[120:121], v[120:121], v[126:127]
	v_mul_f32_e32 v126, 0xbfb8aa3b, v122
	v_mul_f32_e32 v127, 0xbfb8aa3b, v123
	v_exp_f32_e32 v126, v126
	v_exp_f32_e32 v127, v127
	v_cvt_pk_bf16_f32 v119, v120, v121
	v_add_f32_e32 v126, 1.0, v126
	v_add_f32_e32 v127, 1.0, v127
	v_rcp_f32_e32 v126, v126
	v_rcp_f32_e32 v127, v127
	s_nop 0
	v_pk_mul_f32 v[122:123], v[122:123], v[126:127]
	s_nop 0
	v_pk_mul_f32 v[122:123], v[114:115], v[122:123]
	v_pk_mul_f32 v[114:115], v[124:125], v[142:143] op_sel_hi:[1,0]
	v_cvt_pk_bf16_f32 v120, v122, v123
	v_mul_f32_e32 v124, 0xbfb8aa3b, v114
	v_mul_f32_e32 v125, 0xbfb8aa3b, v115
	v_exp_f32_e32 v124, v124
	v_exp_f32_e32 v125, v125
	v_add_f32_e32 v124, 1.0, v124
	v_add_f32_e32 v125, 1.0, v125
	v_rcp_f32_e32 v124, v124
	v_rcp_f32_e32 v125, v125
	s_nop 0
	v_pk_mul_f32 v[114:115], v[114:115], v[124:125]
	s_nop 0
	v_pk_mul_f32 v[116:117], v[116:117], v[114:115]
	v_mov_b64_e32 v[114:115], s[38:39]
	v_mad_i64_i32 v[124:125], s[38:39], v130, s55, v[114:115]
	v_lshl_add_u64 v[124:125], v[124:125], 0, s[8:9]
	v_cvt_pk_bf16_f32 v121, v116, v117
	v_lshlrev_b64 v[116:117], 1, v[134:135]
	v_lshl_add_u64 v[122:123], v[124:125], 0, v[116:117]
	global_store_dwordx2 v[122:123], v[118:119], off
	global_store_dwordx2 v[122:123], v[120:121], off offset:32
	v_or_b32_e32 v118, 16, v130
	v_ashrrev_i32_e32 v119, 31, v118
	v_lshlrev_b64 v[120:121], 6, v[118:119]
	v_lshl_add_u64 v[120:121], s[66:67], 0, v[120:121]
	v_lshl_add_u64 v[120:121], v[120:121], 0, v[132:133]
	global_load_dwordx4 v[120:123], v[120:121], off
	s_waitcnt vmcnt(0)
; #define SCHED __builtin_amdgcn_sched_barrier(0)
; DI float red_fq(float s) { s += __shfl_xor(s, 16); s += __shfl_xor(s, 32); return s; }
; #pragma unroll
;   for (int j = 0; j < 4; ++j) { const int sl = 4 * fq + j; s += (sl >= lo && sl < lo + n) ? v[j] : 0.f; }
;   return red_fq(s); }
; DI float rstd_slots(const float* ssq, int tok, int fq, int lo, int n, float width) {
;   const f32x4 v = *(const f32x4*)(ssq + (size_t)tok * 16 + 4 * fq);
;   return __builtin_amdgcn_rsqf(slots_sum(v, fq, lo, n) / width + EPS);
;   DI void finish(f32x4 (&acc)[2][2][4][2], int tb, int q, int lane) {
;     asm volatile("" : "+v"(lane));
;     const int fr = lane & 15, fq = lane >> 4;
; #pragma unroll
;     for (int ai = 0; ai < 2; ++ai)
; #pragma unroll
;       for (int m = 0; m < 4; ++m) {
;         SCHED;
;         const int tok = tb + ai * 128 + m * 16 + fr;
;         const float rstd = rstd_slots(ssqx, tok, fq, 0, 16, 1024.f);
;         f32x4 a[2];
; #pragma unroll
;         for (int n = 0; n < 2; ++n)
; #pragma unroll
;           for (int j = 0; j < 4; ++j) {
;             const float g = acc[ai][0][m][n][j] * rstd, u = acc[ai][1][m][n][j] * rstd;
;             a[n][j] = g * __builtin_amdgcn_rcpf(1.f + __builtin_amdgcn_exp2f(-g * LOG2E)) * u;
;           }
;         tok_st32(ACT + (size_t)tok * DFF + q * 32, a[0], a[1], fq);
;       }
	v_add_f32_e32 v119, 0, v120
	v_cndmask_b32_e32 v119, 0, v119, vcc
	v_cndmask_b32_e64 v120, 0, v121, s[0:1]
	v_add_f32_e32 v119, v120, v119
	v_cndmask_b32_e64 v120, 0, v122, s[4:5]
	v_add_f32_e32 v119, v120, v119
	v_cndmask_b32_e64 v120, 0, v123, s[6:7]
	v_add_f32_e32 v119, v120, v119
	v_mov_b32_e32 v120, v119
	s_nop 1
	v_permlane16_swap_b32_e32 v120, v119
	v_add_f32_e32 v119, v119, v120
	v_mov_b32_e32 v120, v119
	s_nop 1
	v_permlane32_swap_b32_e32 v120, v119
	v_add_f32_e32 v119, v119, v120
	v_fmamk_f32 v119, v119, 0x3a800000, v181
	v_rsq_f32_e32 v120, v119
	s_nop 0
	v_pk_mul_f32 v[110:111], v[110:111], v[120:121] op_sel_hi:[1,0]
	s_nop 0
	v_mul_f32_e32 v119, 0xbfb8aa3b, v110
	v_exp_f32_e32 v119, v119
	v_pk_mul_f32 v[102:103], v[102:103], v[120:121] op_sel_hi:[1,0]
	v_pk_mul_f32 v[104:105], v[104:105], v[120:121] op_sel_hi:[1,0]
	v_pk_mul_f32 v[106:107], v[106:107], v[120:121] op_sel_hi:[1,0]
	v_add_f32_e32 v119, 1.0, v119
	v_rcp_f32_e32 v122, v119
	v_mul_f32_e32 v119, 0xbfb8aa3b, v111
	v_exp_f32_e32 v119, v119
	v_pk_mul_f32 v[98:99], v[98:99], v[120:121] op_sel_hi:[1,0]
	v_pk_mul_f32 v[100:101], v[100:101], v[120:121] op_sel_hi:[1,0]
	v_add_f32_e32 v119, 1.0, v119
	v_rcp_f32_e32 v123, v119
	s_nop 0
	v_pk_mul_f32 v[110:111], v[110:111], v[122:123]
	s_nop 0
	v_pk_mul_f32 v[102:103], v[102:103], v[110:111]
	v_pk_mul_f32 v[110:111], v[112:113], v[120:121] op_sel_hi:[1,0]
	v_cvt_pk_bf16_f32 v102, v102, v103
	v_mul_f32_e32 v112, 0xbfb8aa3b, v110
	v_mul_f32_e32 v113, 0xbfb8aa3b, v111
	v_exp_f32_e32 v112, v112
	v_exp_f32_e32 v113, v113
	v_add_f32_e32 v112, 1.0, v112
	v_add_f32_e32 v113, 1.0, v113
	v_rcp_f32_e32 v112, v112
	v_rcp_f32_e32 v113, v113
	s_nop 0
	v_pk_mul_f32 v[110:111], v[110:111], v[112:113]
	s_nop 0
	v_pk_mul_f32 v[104:105], v[104:105], v[110:111]
	v_mul_f32_e32 v110, 0xbfb8aa3b, v106
	v_mul_f32_e32 v111, 0xbfb8aa3b, v107
	v_exp_f32_e32 v110, v110
	v_exp_f32_e32 v111, v111
	v_cvt_pk_bf16_f32 v103, v104, v105
	v_add_f32_e32 v110, 1.0, v110
	v_add_f32_e32 v111, 1.0, v111
	v_rcp_f32_e32 v110, v110
	v_rcp_f32_e32 v111, v111
	s_nop 0
	v_pk_mul_f32 v[106:107], v[106:107], v[110:111]
	s_nop 0
	v_pk_mul_f32 v[98:99], v[98:99], v[106:107]
	v_pk_mul_f32 v[106:107], v[108:109], v[120:121] op_sel_hi:[1,0]
	v_cvt_pk_bf16_f32 v98, v98, v99
	v_mul_f32_e32 v108, 0xbfb8aa3b, v106
	v_mul_f32_e32 v109, 0xbfb8aa3b, v107
	v_exp_f32_e32 v108, v108
	v_exp_f32_e32 v109, v109
	v_add_f32_e32 v108, 1.0, v108
	v_add_f32_e32 v109, 1.0, v109
	v_rcp_f32_e32 v108, v108
	v_rcp_f32_e32 v109, v109
	s_nop 0
	v_pk_mul_f32 v[106:107], v[106:107], v[108:109]
	s_nop 0
	v_pk_mul_f32 v[100:101], v[100:101], v[106:107]
	v_mad_i64_i32 v[106:107], s[38:39], v118, s55, v[114:115]
	v_lshl_add_u64 v[106:107], v[106:107], 0, s[8:9]
	v_cvt_pk_bf16_f32 v99, v100, v101
	v_lshl_add_u64 v[100:101], v[106:107], 0, v[116:117]
	global_store_dwordx2 v[100:101], v[102:103], off
	global_store_dwordx2 v[100:101], v[98:99], off offset:32
	v_or_b32_e32 v98, 32, v130
	v_ashrrev_i32_e32 v99, 31, v98
	v_lshlrev_b64 v[100:101], 6, v[98:99]
	v_lshl_add_u64 v[100:101], s[66:67], 0, v[100:101]
	v_lshl_add_u64 v[100:101], v[100:101], 0, v[132:133]
	global_load_dwordx4 v[100:103], v[100:101], off
	s_waitcnt vmcnt(0)
	v_add_f32_e32 v99, 0, v100
	v_cndmask_b32_e32 v99, 0, v99, vcc
	v_cndmask_b32_e64 v100, 0, v101, s[0:1]
	v_add_f32_e32 v99, v100, v99
	v_cndmask_b32_e64 v100, 0, v102, s[4:5]
	v_add_f32_e32 v99, v100, v99
	v_cndmask_b32_e64 v100, 0, v103, s[6:7]
	v_add_f32_e32 v99, v100, v99
	v_mov_b32_e32 v100, v99
	s_nop 1
	v_permlane16_swap_b32_e32 v100, v99
	v_add_f32_e32 v99, v99, v100
	v_mov_b32_e32 v100, v99
	s_nop 1
	v_permlane32_swap_b32_e32 v100, v99
	v_add_f32_e32 v99, v99, v100
	v_fmamk_f32 v99, v99, 0x3a800000, v181
	v_rsq_f32_e32 v100, v99
	s_nop 0
	v_pk_mul_f32 v[94:95], v[94:95], v[100:101] op_sel_hi:[1,0]
	s_nop 0
	v_mul_f32_e32 v99, 0xbfb8aa3b, v94
	v_exp_f32_e32 v99, v99
	v_pk_mul_f32 v[86:87], v[86:87], v[100:101] op_sel_hi:[1,0]
	v_pk_mul_f32 v[88:89], v[88:89], v[100:101] op_sel_hi:[1,0]
	v_pk_mul_f32 v[90:91], v[90:91], v[100:101] op_sel_hi:[1,0]
	v_add_f32_e32 v99, 1.0, v99
	v_rcp_f32_e32 v102, v99
	v_mul_f32_e32 v99, 0xbfb8aa3b, v95
	v_exp_f32_e32 v99, v99
	v_pk_mul_f32 v[82:83], v[82:83], v[100:101] op_sel_hi:[1,0]
	v_pk_mul_f32 v[84:85], v[84:85], v[100:101] op_sel_hi:[1,0]
	v_add_f32_e32 v99, 1.0, v99
	v_rcp_f32_e32 v103, v99
	s_nop 0
	v_pk_mul_f32 v[94:95], v[94:95], v[102:103]
	s_nop 0
	v_pk_mul_f32 v[86:87], v[86:87], v[94:95]
	v_pk_mul_f32 v[94:95], v[96:97], v[100:101] op_sel_hi:[1,0]
	v_cvt_pk_bf16_f32 v86, v86, v87
	v_mul_f32_e32 v96, 0xbfb8aa3b, v94
	v_mul_f32_e32 v97, 0xbfb8aa3b, v95
	v_exp_f32_e32 v96, v96
	v_exp_f32_e32 v97, v97
	v_add_f32_e32 v96, 1.0, v96
	v_add_f32_e32 v97, 1.0, v97
	v_rcp_f32_e32 v96, v96
	v_rcp_f32_e32 v97, v97
	s_nop 0
	v_pk_mul_f32 v[94:95], v[94:95], v[96:97]
	s_nop 0
	v_pk_mul_f32 v[88:89], v[88:89], v[94:95]
	v_mul_f32_e32 v94, 0xbfb8aa3b, v90
	v_mul_f32_e32 v95, 0xbfb8aa3b, v91
	v_exp_f32_e32 v94, v94
	v_exp_f32_e32 v95, v95
	v_cvt_pk_bf16_f32 v87, v88, v89
	v_add_f32_e32 v94, 1.0, v94
	v_add_f32_e32 v95, 1.0, v95
	v_rcp_f32_e32 v94, v94
	v_rcp_f32_e32 v95, v95
	s_nop 0
	v_pk_mul_f32 v[90:91], v[90:91], v[94:95]
	s_nop 0
	v_pk_mul_f32 v[82:83], v[82:83], v[90:91]
	v_pk_mul_f32 v[90:91], v[92:93], v[100:101] op_sel_hi:[1,0]
	v_cvt_pk_bf16_f32 v82, v82, v83
	v_mul_f32_e32 v92, 0xbfb8aa3b, v90
	v_mul_f32_e32 v93, 0xbfb8aa3b, v91
	v_exp_f32_e32 v92, v92
	v_exp_f32_e32 v93, v93
	v_add_f32_e32 v92, 1.0, v92
	v_add_f32_e32 v93, 1.0, v93
	v_rcp_f32_e32 v92, v92
	v_rcp_f32_e32 v93, v93
	s_nop 0
	v_pk_mul_f32 v[90:91], v[90:91], v[92:93]
	s_nop 0
	v_pk_mul_f32 v[84:85], v[84:85], v[90:91]
	v_mad_i64_i32 v[90:91], s[38:39], v98, s55, v[114:115]
	v_lshl_add_u64 v[90:91], v[90:91], 0, s[8:9]
	v_cvt_pk_bf16_f32 v83, v84, v85
	v_lshl_add_u64 v[84:85], v[90:91], 0, v[116:117]
	global_store_dwordx2 v[84:85], v[86:87], off
	global_store_dwordx2 v[84:85], v[82:83], off offset:32
	v_or_b32_e32 v82, 48, v130
	v_ashrrev_i32_e32 v83, 31, v82
	v_lshlrev_b64 v[84:85], 6, v[82:83]
	v_lshl_add_u64 v[84:85], s[66:67], 0, v[84:85]
	v_lshl_add_u64 v[84:85], v[84:85], 0, v[132:133]
	global_load_dwordx4 v[84:87], v[84:85], off
	s_waitcnt vmcnt(0)
; #define SCHED __builtin_amdgcn_sched_barrier(0)
; DI float red_fq(float s) { s += __shfl_xor(s, 16); s += __shfl_xor(s, 32); return s; }
; #pragma unroll
;   for (int j = 0; j < 4; ++j) { const int sl = 4 * fq + j; s += (sl >= lo && sl < lo + n) ? v[j] : 0.f; }
;   return red_fq(s); }
; DI float rstd_slots(const float* ssq, int tok, int fq, int lo, int n, float width) {
;   const f32x4 v = *(const f32x4*)(ssq + (size_t)tok * 16 + 4 * fq);
;   return __builtin_amdgcn_rsqf(slots_sum(v, fq, lo, n) / width + EPS);
;   DI void finish(f32x4 (&acc)[2][2][4][2], int tb, int q, int lane) {
;     asm volatile("" : "+v"(lane));
;     const int fr = lane & 15, fq = lane >> 4;
; #pragma unroll
;     for (int ai = 0; ai < 2; ++ai)
; #pragma unroll
;       for (int m = 0; m < 4; ++m) {
;         SCHED;
;         const int tok = tb + ai * 128 + m * 16 + fr;
;         const float rstd = rstd_slots(ssqx, tok, fq, 0, 16, 1024.f);
;         f32x4 a[2];
; #pragma unroll
;         for (int n = 0; n < 2; ++n)
; #pragma unroll
;           for (int j = 0; j < 4; ++j) {
;             const float g = acc[ai][0][m][n][j] * rstd, u = acc[ai][1][m][n][j] * rstd;
;             a[n][j] = g * __builtin_amdgcn_rcpf(1.f + __builtin_amdgcn_exp2f(-g * LOG2E)) * u;
;           }
;         tok_st32(ACT + (size_t)tok * DFF + q * 32, a[0], a[1], fq);
;       }
	v_add_f32_e32 v83, 0, v84
	v_cndmask_b32_e32 v83, 0, v83, vcc
	v_cndmask_b32_e64 v84, 0, v85, s[0:1]
	v_add_f32_e32 v83, v84, v83
	v_cndmask_b32_e64 v84, 0, v86, s[4:5]
	v_add_f32_e32 v83, v84, v83
	v_cndmask_b32_e64 v84, 0, v87, s[6:7]
	v_add_f32_e32 v83, v84, v83
	v_mov_b32_e32 v84, v83
	s_nop 1
	v_permlane16_swap_b32_e32 v84, v83
	v_add_f32_e32 v83, v83, v84
	v_mov_b32_e32 v84, v83
	s_nop 1
	v_permlane32_swap_b32_e32 v84, v83
	v_add_f32_e32 v83, v83, v84
	v_fmamk_f32 v83, v83, 0x3a800000, v181
	v_rsq_f32_e32 v84, v83
	s_nop 0
	v_pk_mul_f32 v[78:79], v[78:79], v[84:85] op_sel_hi:[1,0]
	s_nop 0
	v_mul_f32_e32 v83, 0xbfb8aa3b, v78
	v_exp_f32_e32 v83, v83
	v_pk_mul_f32 v[70:71], v[70:71], v[84:85] op_sel_hi:[1,0]
	v_pk_mul_f32 v[72:73], v[72:73], v[84:85] op_sel_hi:[1,0]
	v_pk_mul_f32 v[74:75], v[74:75], v[84:85] op_sel_hi:[1,0]
	v_add_f32_e32 v83, 1.0, v83
	v_rcp_f32_e32 v86, v83
	v_mul_f32_e32 v83, 0xbfb8aa3b, v79
	v_exp_f32_e32 v83, v83
	v_pk_mul_f32 v[66:67], v[66:67], v[84:85] op_sel_hi:[1,0]
	v_pk_mul_f32 v[68:69], v[68:69], v[84:85] op_sel_hi:[1,0]
	v_add_f32_e32 v83, 1.0, v83
	v_rcp_f32_e32 v87, v83
	s_nop 0
	v_pk_mul_f32 v[78:79], v[78:79], v[86:87]
	s_nop 0
	v_pk_mul_f32 v[70:71], v[70:71], v[78:79]
	v_pk_mul_f32 v[78:79], v[80:81], v[84:85] op_sel_hi:[1,0]
	v_cvt_pk_bf16_f32 v70, v70, v71
	v_mul_f32_e32 v80, 0xbfb8aa3b, v78
	v_mul_f32_e32 v81, 0xbfb8aa3b, v79
	v_exp_f32_e32 v80, v80
	v_exp_f32_e32 v81, v81
	v_add_f32_e32 v80, 1.0, v80
	v_add_f32_e32 v81, 1.0, v81
	v_rcp_f32_e32 v80, v80
	v_rcp_f32_e32 v81, v81
	s_nop 0
	v_pk_mul_f32 v[78:79], v[78:79], v[80:81]
	s_nop 0
	v_pk_mul_f32 v[72:73], v[72:73], v[78:79]
	v_mul_f32_e32 v78, 0xbfb8aa3b, v74
	v_mul_f32_e32 v79, 0xbfb8aa3b, v75
	v_exp_f32_e32 v78, v78
	v_exp_f32_e32 v79, v79
	v_cvt_pk_bf16_f32 v71, v72, v73
	v_add_f32_e32 v78, 1.0, v78
	v_add_f32_e32 v79, 1.0, v79
	v_rcp_f32_e32 v78, v78
	v_rcp_f32_e32 v79, v79
	s_nop 0
	v_pk_mul_f32 v[74:75], v[74:75], v[78:79]
	s_nop 0
	v_pk_mul_f32 v[66:67], v[66:67], v[74:75]
	v_pk_mul_f32 v[74:75], v[76:77], v[84:85] op_sel_hi:[1,0]
	v_cvt_pk_bf16_f32 v66, v66, v67
	v_mul_f32_e32 v76, 0xbfb8aa3b, v74
	v_mul_f32_e32 v77, 0xbfb8aa3b, v75
	v_exp_f32_e32 v76, v76
	v_exp_f32_e32 v77, v77
	v_add_f32_e32 v76, 1.0, v76
	v_add_f32_e32 v77, 1.0, v77
	v_rcp_f32_e32 v76, v76
	v_rcp_f32_e32 v77, v77
	s_nop 0
	v_pk_mul_f32 v[74:75], v[74:75], v[76:77]
	s_nop 0
	v_pk_mul_f32 v[68:69], v[68:69], v[74:75]
	v_mad_i64_i32 v[74:75], s[38:39], v82, s55, v[114:115]
	v_lshl_add_u64 v[74:75], v[74:75], 0, s[8:9]
	v_cvt_pk_bf16_f32 v67, v68, v69
	v_lshl_add_u64 v[68:69], v[74:75], 0, v[116:117]
	global_store_dwordx2 v[68:69], v[70:71], off
	global_store_dwordx2 v[68:69], v[66:67], off offset:32
	v_add_u32_e32 v66, 0x80, v130
	v_ashrrev_i32_e32 v67, 31, v66
	v_lshlrev_b64 v[68:69], 6, v[66:67]
	v_lshl_add_u64 v[68:69], s[66:67], 0, v[68:69]
	v_lshl_add_u64 v[68:69], v[68:69], 0, v[132:133]
	global_load_dwordx4 v[68:71], v[68:69], off
	s_waitcnt vmcnt(0)
	v_add_f32_e32 v67, 0, v68
	v_cndmask_b32_e32 v67, 0, v67, vcc
	v_cndmask_b32_e64 v68, 0, v69, s[0:1]
	v_add_f32_e32 v67, v68, v67
	v_cndmask_b32_e64 v68, 0, v70, s[4:5]
	v_add_f32_e32 v67, v68, v67
	v_cndmask_b32_e64 v68, 0, v71, s[6:7]
	v_add_f32_e32 v67, v68, v67
	v_mov_b32_e32 v68, v67
	s_nop 1
	v_permlane16_swap_b32_e32 v68, v67
	v_add_f32_e32 v67, v67, v68
	v_mov_b32_e32 v68, v67
	s_nop 1
	v_permlane32_swap_b32_e32 v68, v67
	v_add_f32_e32 v67, v67, v68
	v_fmamk_f32 v67, v67, 0x3a800000, v181
	v_rsq_f32_e32 v68, v67
	s_nop 0
	v_pk_mul_f32 v[62:63], v[62:63], v[68:69] op_sel_hi:[1,0]
	s_nop 0
	v_mul_f32_e32 v67, 0xbfb8aa3b, v62
	v_exp_f32_e32 v67, v67
	v_pk_mul_f32 v[54:55], v[54:55], v[68:69] op_sel_hi:[1,0]
	v_pk_mul_f32 v[56:57], v[56:57], v[68:69] op_sel_hi:[1,0]
	v_pk_mul_f32 v[58:59], v[58:59], v[68:69] op_sel_hi:[1,0]
	v_add_f32_e32 v67, 1.0, v67
	v_rcp_f32_e32 v70, v67
	v_mul_f32_e32 v67, 0xbfb8aa3b, v63
	v_exp_f32_e32 v67, v67
	v_pk_mul_f32 v[50:51], v[50:51], v[68:69] op_sel_hi:[1,0]
	v_pk_mul_f32 v[52:53], v[52:53], v[68:69] op_sel_hi:[1,0]
	v_add_f32_e32 v67, 1.0, v67
	v_rcp_f32_e32 v71, v67
	s_nop 0
	v_pk_mul_f32 v[62:63], v[62:63], v[70:71]
	s_nop 0
	v_pk_mul_f32 v[54:55], v[54:55], v[62:63]
	v_pk_mul_f32 v[62:63], v[64:65], v[68:69] op_sel_hi:[1,0]
	v_cvt_pk_bf16_f32 v54, v54, v55
	v_mul_f32_e32 v64, 0xbfb8aa3b, v62
	v_mul_f32_e32 v65, 0xbfb8aa3b, v63
	v_exp_f32_e32 v64, v64
	v_exp_f32_e32 v65, v65
	v_add_f32_e32 v64, 1.0, v64
	v_add_f32_e32 v65, 1.0, v65
	v_rcp_f32_e32 v64, v64
	v_rcp_f32_e32 v65, v65
	s_nop 0
	v_pk_mul_f32 v[62:63], v[62:63], v[64:65]
	s_nop 0
	v_pk_mul_f32 v[56:57], v[56:57], v[62:63]
	v_mul_f32_e32 v62, 0xbfb8aa3b, v58
	v_mul_f32_e32 v63, 0xbfb8aa3b, v59
	v_exp_f32_e32 v62, v62
	v_exp_f32_e32 v63, v63
	v_cvt_pk_bf16_f32 v55, v56, v57
	v_add_f32_e32 v62, 1.0, v62
	v_add_f32_e32 v63, 1.0, v63
	v_rcp_f32_e32 v62, v62
	v_rcp_f32_e32 v63, v63
	s_nop 0
	v_pk_mul_f32 v[58:59], v[58:59], v[62:63]
	s_nop 0
	v_pk_mul_f32 v[50:51], v[50:51], v[58:59]
	v_pk_mul_f32 v[58:59], v[60:61], v[68:69] op_sel_hi:[1,0]
	v_cvt_pk_bf16_f32 v50, v50, v51
	v_mul_f32_e32 v60, 0xbfb8aa3b, v58
	v_mul_f32_e32 v61, 0xbfb8aa3b, v59
	v_exp_f32_e32 v60, v60
	v_exp_f32_e32 v61, v61
	v_add_f32_e32 v60, 1.0, v60
	v_add_f32_e32 v61, 1.0, v61
	v_rcp_f32_e32 v60, v60
	v_rcp_f32_e32 v61, v61
	s_nop 0
	v_pk_mul_f32 v[58:59], v[58:59], v[60:61]
	s_nop 0
	v_pk_mul_f32 v[52:53], v[52:53], v[58:59]
	v_mad_i64_i32 v[58:59], s[38:39], v66, s55, v[114:115]
	v_lshl_add_u64 v[58:59], v[58:59], 0, s[8:9]
	v_cvt_pk_bf16_f32 v51, v52, v53
	v_lshl_add_u64 v[52:53], v[58:59], 0, v[116:117]
	global_store_dwordx2 v[52:53], v[54:55], off
	global_store_dwordx2 v[52:53], v[50:51], off offset:32
	v_add_u32_e32 v50, 0x90, v130
	v_ashrrev_i32_e32 v51, 31, v50
	v_lshlrev_b64 v[52:53], 6, v[50:51]
	v_lshl_add_u64 v[52:53], s[66:67], 0, v[52:53]
	v_lshl_add_u64 v[52:53], v[52:53], 0, v[132:133]
	global_load_dwordx4 v[52:55], v[52:53], off
	s_waitcnt vmcnt(0)
; #define SCHED __builtin_amdgcn_sched_barrier(0)
; DI float red_fq(float s) { s += __shfl_xor(s, 16); s += __shfl_xor(s, 32); return s; }
; #pragma unroll
;   for (int j = 0; j < 4; ++j) { const int sl = 4 * fq + j; s += (sl >= lo && sl < lo + n) ? v[j] : 0.f; }
;   return red_fq(s); }
; DI float rstd_slots(const float* ssq, int tok, int fq, int lo, int n, float width) {
;   const f32x4 v = *(const f32x4*)(ssq + (size_t)tok * 16 + 4 * fq);
;   return __builtin_amdgcn_rsqf(slots_sum(v, fq, lo, n) / width + EPS);
;   DI void finish(f32x4 (&acc)[2][2][4][2], int tb, int q, int lane) {
;     asm volatile("" : "+v"(lane));
;     const int fr = lane & 15, fq = lane >> 4;
; #pragma unroll
;     for (int ai = 0; ai < 2; ++ai)
; #pragma unroll
;       for (int m = 0; m < 4; ++m) {
;         SCHED;
;         const int tok = tb + ai * 128 + m * 16 + fr;
;         const float rstd = rstd_slots(ssqx, tok, fq, 0, 16, 1024.f);
;         f32x4 a[2];
; #pragma unroll
;         for (int n = 0; n < 2; ++n)
; #pragma unroll
;           for (int j = 0; j < 4; ++j) {
;             const float g = acc[ai][0][m][n][j] * rstd, u = acc[ai][1][m][n][j] * rstd;
;             a[n][j] = g * __builtin_amdgcn_rcpf(1.f + __builtin_amdgcn_exp2f(-g * LOG2E)) * u;
;           }
;         tok_st32(ACT + (size_t)tok * DFF + q * 32, a[0], a[1], fq);
;       }
	v_add_f32_e32 v51, 0, v52
	v_cndmask_b32_e32 v51, 0, v51, vcc
	v_cndmask_b32_e64 v52, 0, v53, s[0:1]
	v_add_f32_e32 v51, v52, v51
	v_cndmask_b32_e64 v52, 0, v54, s[4:5]
	v_add_f32_e32 v51, v52, v51
	v_cndmask_b32_e64 v52, 0, v55, s[6:7]
	v_add_f32_e32 v51, v52, v51
	v_mov_b32_e32 v52, v51
	s_nop 1
	v_permlane16_swap_b32_e32 v52, v51
	v_add_f32_e32 v51, v51, v52
	v_mov_b32_e32 v52, v51
	s_nop 1
	v_permlane32_swap_b32_e32 v52, v51
	v_add_f32_e32 v51, v51, v52
	v_fmamk_f32 v51, v51, 0x3a800000, v181
	v_rsq_f32_e32 v52, v51
	s_nop 0
	v_pk_mul_f32 v[46:47], v[46:47], v[52:53] op_sel_hi:[1,0]
	s_nop 0
	v_mul_f32_e32 v51, 0xbfb8aa3b, v46
	v_exp_f32_e32 v51, v51
	v_pk_mul_f32 v[38:39], v[38:39], v[52:53] op_sel_hi:[1,0]
	v_pk_mul_f32 v[40:41], v[40:41], v[52:53] op_sel_hi:[1,0]
	v_pk_mul_f32 v[42:43], v[42:43], v[52:53] op_sel_hi:[1,0]
	v_add_f32_e32 v51, 1.0, v51
	v_rcp_f32_e32 v54, v51
	v_mul_f32_e32 v51, 0xbfb8aa3b, v47
	v_exp_f32_e32 v51, v51
	v_pk_mul_f32 v[34:35], v[34:35], v[52:53] op_sel_hi:[1,0]
	v_pk_mul_f32 v[36:37], v[36:37], v[52:53] op_sel_hi:[1,0]
	v_add_f32_e32 v51, 1.0, v51
	v_rcp_f32_e32 v55, v51
	s_nop 0
	v_pk_mul_f32 v[46:47], v[46:47], v[54:55]
	s_nop 0
	v_pk_mul_f32 v[38:39], v[38:39], v[46:47]
	v_pk_mul_f32 v[46:47], v[48:49], v[52:53] op_sel_hi:[1,0]
	v_cvt_pk_bf16_f32 v38, v38, v39
	v_mul_f32_e32 v48, 0xbfb8aa3b, v46
	v_mul_f32_e32 v49, 0xbfb8aa3b, v47
	v_exp_f32_e32 v48, v48
	v_exp_f32_e32 v49, v49
	v_add_f32_e32 v48, 1.0, v48
	v_add_f32_e32 v49, 1.0, v49
	v_rcp_f32_e32 v48, v48
	v_rcp_f32_e32 v49, v49
	s_nop 0
	v_pk_mul_f32 v[46:47], v[46:47], v[48:49]
	s_nop 0
	v_pk_mul_f32 v[40:41], v[40:41], v[46:47]
	v_mul_f32_e32 v46, 0xbfb8aa3b, v42
	v_mul_f32_e32 v47, 0xbfb8aa3b, v43
	v_exp_f32_e32 v46, v46
	v_exp_f32_e32 v47, v47
	v_cvt_pk_bf16_f32 v39, v40, v41
	v_add_f32_e32 v46, 1.0, v46
	v_add_f32_e32 v47, 1.0, v47
	v_rcp_f32_e32 v46, v46
	v_rcp_f32_e32 v47, v47
	s_nop 0
	v_pk_mul_f32 v[42:43], v[42:43], v[46:47]
	s_nop 0
	v_pk_mul_f32 v[34:35], v[34:35], v[42:43]
	v_pk_mul_f32 v[42:43], v[44:45], v[52:53] op_sel_hi:[1,0]
	v_cvt_pk_bf16_f32 v34, v34, v35
	v_mul_f32_e32 v44, 0xbfb8aa3b, v42
	v_mul_f32_e32 v45, 0xbfb8aa3b, v43
	v_exp_f32_e32 v44, v44
	v_exp_f32_e32 v45, v45
	v_add_f32_e32 v44, 1.0, v44
	v_add_f32_e32 v45, 1.0, v45
	v_rcp_f32_e32 v44, v44
	v_rcp_f32_e32 v45, v45
	s_nop 0
	v_pk_mul_f32 v[42:43], v[42:43], v[44:45]
	s_nop 0
	v_pk_mul_f32 v[36:37], v[36:37], v[42:43]
	v_mad_i64_i32 v[42:43], s[38:39], v50, s55, v[114:115]
	v_lshl_add_u64 v[42:43], v[42:43], 0, s[8:9]
	v_cvt_pk_bf16_f32 v35, v36, v37
	v_lshl_add_u64 v[36:37], v[42:43], 0, v[116:117]
	global_store_dwordx2 v[36:37], v[38:39], off
	global_store_dwordx2 v[36:37], v[34:35], off offset:32
	v_add_u32_e32 v34, 0xa0, v130
	v_ashrrev_i32_e32 v35, 31, v34
	v_lshlrev_b64 v[36:37], 6, v[34:35]
	v_lshl_add_u64 v[36:37], s[66:67], 0, v[36:37]
	v_lshl_add_u64 v[36:37], v[36:37], 0, v[132:133]
	global_load_dwordx4 v[36:39], v[36:37], off
	s_waitcnt vmcnt(0)
; #define SCHED __builtin_amdgcn_sched_barrier(0)
; DI float red_fq(float s) { s += __shfl_xor(s, 16); s += __shfl_xor(s, 32); return s; }
; #pragma unroll
;   for (int j = 0; j < 4; ++j) { const int sl = 4 * fq + j; s += (sl >= lo && sl < lo + n) ? v[j] : 0.f; }
;   return red_fq(s); }
; DI float rstd_slots(const float* ssq, int tok, int fq, int lo, int n, float width) {
;   const f32x4 v = *(const f32x4*)(ssq + (size_t)tok * 16 + 4 * fq);
;   return __builtin_amdgcn_rsqf(slots_sum(v, fq, lo, n) / width + EPS);
;   DI void finish(f32x4 (&acc)[2][2][4][2], int tb, int q, int lane) {
;     asm volatile("" : "+v"(lane));
;     const int fr = lane & 15, fq = lane >> 4;
; #pragma unroll
;     for (int ai = 0; ai < 2; ++ai)
; #pragma unroll
;       for (int m = 0; m < 4; ++m) {
;         SCHED;
;         const int tok = tb + ai * 128 + m * 16 + fr;
;         const float rstd = rstd_slots(ssqx, tok, fq, 0, 16, 1024.f);
;         f32x4 a[2];
; #pragma unroll
;         for (int n = 0; n < 2; ++n)
; #pragma unroll
;           for (int j = 0; j < 4; ++j) {
;             const float g = acc[ai][0][m][n][j] * rstd, u = acc[ai][1][m][n][j] * rstd;
;             a[n][j] = g * __builtin_amdgcn_rcpf(1.f + __builtin_amdgcn_exp2f(-g * LOG2E)) * u;
;           }
;         tok_st32(ACT + (size_t)tok * DFF + q * 32, a[0], a[1], fq);
;       }
	v_add_f32_e32 v35, 0, v36
	v_cndmask_b32_e32 v35, 0, v35, vcc
	v_cndmask_b32_e64 v36, 0, v37, s[0:1]
	v_add_f32_e32 v35, v36, v35
	v_cndmask_b32_e64 v36, 0, v38, s[4:5]
	v_add_f32_e32 v35, v36, v35
	v_cndmask_b32_e64 v36, 0, v39, s[6:7]
	v_add_f32_e32 v35, v36, v35
	v_mov_b32_e32 v36, v35
	s_nop 1
	v_permlane16_swap_b32_e32 v36, v35
	v_add_f32_e32 v35, v35, v36
	v_mov_b32_e32 v36, v35
	s_nop 1
	v_permlane32_swap_b32_e32 v36, v35
	v_add_f32_e32 v35, v35, v36
	v_fmamk_f32 v35, v35, 0x3a800000, v181
	v_rsq_f32_e32 v36, v35
	s_nop 0
	v_pk_mul_f32 v[30:31], v[30:31], v[36:37] op_sel_hi:[1,0]
	s_nop 0
	v_mul_f32_e32 v35, 0xbfb8aa3b, v30
	v_exp_f32_e32 v35, v35
	v_pk_mul_f32 v[22:23], v[22:23], v[36:37] op_sel_hi:[1,0]
	v_pk_mul_f32 v[24:25], v[24:25], v[36:37] op_sel_hi:[1,0]
	v_pk_mul_f32 v[26:27], v[26:27], v[36:37] op_sel_hi:[1,0]
	v_add_f32_e32 v35, 1.0, v35
	v_rcp_f32_e32 v38, v35
	v_mul_f32_e32 v35, 0xbfb8aa3b, v31
	v_exp_f32_e32 v35, v35
	v_pk_mul_f32 v[18:19], v[18:19], v[36:37] op_sel_hi:[1,0]
	v_pk_mul_f32 v[20:21], v[20:21], v[36:37] op_sel_hi:[1,0]
	v_add_f32_e32 v35, 1.0, v35
	v_rcp_f32_e32 v39, v35
	s_nop 0
	v_pk_mul_f32 v[30:31], v[30:31], v[38:39]
	s_nop 0
	v_pk_mul_f32 v[22:23], v[22:23], v[30:31]
	v_pk_mul_f32 v[30:31], v[32:33], v[36:37] op_sel_hi:[1,0]
	v_cvt_pk_bf16_f32 v22, v22, v23
	v_mul_f32_e32 v32, 0xbfb8aa3b, v30
	v_mul_f32_e32 v33, 0xbfb8aa3b, v31
	v_exp_f32_e32 v32, v32
	v_exp_f32_e32 v33, v33
	v_add_f32_e32 v32, 1.0, v32
	v_add_f32_e32 v33, 1.0, v33
	v_rcp_f32_e32 v32, v32
	v_rcp_f32_e32 v33, v33
	s_nop 0
	v_pk_mul_f32 v[30:31], v[30:31], v[32:33]
	s_nop 0
	v_pk_mul_f32 v[24:25], v[24:25], v[30:31]
	v_mul_f32_e32 v30, 0xbfb8aa3b, v26
	v_mul_f32_e32 v31, 0xbfb8aa3b, v27
	v_exp_f32_e32 v30, v30
	v_exp_f32_e32 v31, v31
	v_cvt_pk_bf16_f32 v23, v24, v25
	v_add_f32_e32 v30, 1.0, v30
	v_add_f32_e32 v31, 1.0, v31
	v_rcp_f32_e32 v30, v30
	v_rcp_f32_e32 v31, v31
	s_nop 0
	v_pk_mul_f32 v[26:27], v[26:27], v[30:31]
	s_nop 0
	v_pk_mul_f32 v[18:19], v[18:19], v[26:27]
	v_pk_mul_f32 v[26:27], v[28:29], v[36:37] op_sel_hi:[1,0]
	v_cvt_pk_bf16_f32 v18, v18, v19
	v_mul_f32_e32 v28, 0xbfb8aa3b, v26
	v_mul_f32_e32 v29, 0xbfb8aa3b, v27
	v_exp_f32_e32 v28, v28
	v_exp_f32_e32 v29, v29
	v_add_f32_e32 v28, 1.0, v28
	v_add_f32_e32 v29, 1.0, v29
	v_rcp_f32_e32 v28, v28
	v_rcp_f32_e32 v29, v29
	s_nop 0
	v_pk_mul_f32 v[26:27], v[26:27], v[28:29]
	s_nop 0
	v_pk_mul_f32 v[20:21], v[20:21], v[26:27]
	v_mad_i64_i32 v[26:27], s[38:39], v34, s55, v[114:115]
	v_lshl_add_u64 v[26:27], v[26:27], 0, s[8:9]
	v_cvt_pk_bf16_f32 v19, v20, v21
	v_lshl_add_u64 v[20:21], v[26:27], 0, v[116:117]
	global_store_dwordx2 v[20:21], v[22:23], off
	global_store_dwordx2 v[20:21], v[18:19], off offset:32
	v_add_u32_e32 v22, 0xb0, v130
	v_ashrrev_i32_e32 v23, 31, v22
	v_lshlrev_b64 v[18:19], 6, v[22:23]
	v_lshl_add_u64 v[18:19], s[66:67], 0, v[18:19]
	v_lshl_add_u64 v[18:19], v[18:19], 0, v[132:133]
	global_load_dwordx4 v[18:21], v[18:19], off
	v_readlane_b32 s76, v248, 5
	v_readlane_b32 s74, v248, 7
	v_readlane_b32 s77, v248, 6
	v_readlane_b32 s75, v248, 8
	s_waitcnt vmcnt(0)
	v_add_f32_e32 v18, 0, v18
	v_cndmask_b32_e64 v19, 0, v19, s[0:1]
	v_cndmask_b32_e32 v18, 0, v18, vcc
	v_cndmask_b32_e64 v20, 0, v20, s[4:5]
	v_add_f32_e32 v18, v19, v18
	v_cndmask_b32_e64 v21, 0, v21, s[6:7]
	v_add_f32_e32 v18, v20, v18
	v_add_f32_e32 v18, v21, v18
	ds_bpermute_b32 v0, v0, v18
	s_andn2_b64 vcc, exec, s[22:23]
	s_waitcnt lgkmcnt(0)
	v_add_f32_e32 v0, v18, v0
	ds_bpermute_b32 v20, v140, v0
	v_mad_i64_i32 v[18:19], s[0:1], v22, s55, v[114:115]
	v_lshl_add_u64 v[18:19], v[18:19], 0, s[8:9]
	v_lshl_add_u64 v[18:19], v[18:19], 0, v[116:117]
	s_waitcnt lgkmcnt(0)
	v_add_f32_e32 v0, v0, v20
	v_fmamk_f32 v0, v0, 0x3a800000, v181
	v_rsq_f32_e32 v0, v0
	s_mov_b64 s[0:1], -1
	v_pk_mul_f32 v[14:15], v[14:15], v[0:1] op_sel_hi:[1,0]
	v_pk_mul_f32 v[16:17], v[16:17], v[0:1] op_sel_hi:[1,0]
	v_pk_mul_f32 v[6:7], v[6:7], v[0:1] op_sel_hi:[1,0]
	v_pk_mul_f32 v[8:9], v[8:9], v[0:1] op_sel_hi:[1,0]
	v_pk_mul_f32 v[10:11], v[10:11], v[0:1] op_sel_hi:[1,0]
	v_pk_mul_f32 v[2:3], v[2:3], v[0:1] op_sel_hi:[1,0]
	v_pk_mul_f32 v[12:13], v[12:13], v[0:1] op_sel_hi:[1,0]
	v_pk_mul_f32 v[4:5], v[4:5], v[0:1] op_sel_hi:[1,0]
	v_mul_f32_e32 v0, 0xbfb8aa3b, v14
	v_mul_f32_e32 v20, 0xbfb8aa3b, v15
	v_mul_f32_e32 v21, 0xbfb8aa3b, v16
	v_mul_f32_e32 v22, 0xbfb8aa3b, v17
	v_mul_f32_e32 v23, 0xbfb8aa3b, v10
	v_mul_f32_e32 v24, 0xbfb8aa3b, v11
	v_mul_f32_e32 v25, 0xbfb8aa3b, v12
	v_mul_f32_e32 v26, 0xbfb8aa3b, v13
	v_exp_f32_e32 v0, v0
	v_exp_f32_e32 v20, v20
	v_exp_f32_e32 v21, v21
	v_exp_f32_e32 v22, v22
	v_exp_f32_e32 v23, v23
	v_exp_f32_e32 v24, v24
	v_exp_f32_e32 v25, v25
	v_exp_f32_e32 v26, v26
	v_add_f32_e32 v0, 1.0, v0
	v_add_f32_e32 v27, 1.0, v20
	v_add_f32_e32 v28, 1.0, v21
	v_add_f32_e32 v29, 1.0, v22
	v_add_f32_e32 v30, 1.0, v23
	v_add_f32_e32 v31, 1.0, v24
	v_add_f32_e32 v32, 1.0, v25
	v_add_f32_e32 v33, 1.0, v26
	v_rcp_f32_e32 v20, v0
	v_rcp_f32_e32 v21, v27
	v_rcp_f32_e32 v22, v28
	v_rcp_f32_e32 v23, v29
	v_rcp_f32_e32 v24, v30
	v_rcp_f32_e32 v25, v31
	v_rcp_f32_e32 v26, v32
	v_rcp_f32_e32 v27, v33
	v_pk_mul_f32 v[14:15], v[14:15], v[20:21]
	v_pk_mul_f32 v[16:17], v[16:17], v[22:23]
	v_pk_mul_f32 v[10:11], v[10:11], v[24:25]
	v_pk_mul_f32 v[12:13], v[12:13], v[26:27]
	v_pk_mul_f32 v[6:7], v[6:7], v[14:15]
	v_pk_mul_f32 v[8:9], v[8:9], v[16:17]
	v_pk_mul_f32 v[2:3], v[2:3], v[10:11]
	v_pk_mul_f32 v[4:5], v[4:5], v[12:13]
	v_cvt_pk_bf16_f32 v6, v6, v7
	v_cvt_pk_bf16_f32 v7, v8, v9
	v_cvt_pk_bf16_f32 v2, v2, v3
	v_cvt_pk_bf16_f32 v3, v4, v5
	global_store_dwordx2 v[18:19], v[6:7], off
	global_store_dwordx2 v[18:19], v[2:3], off offset:32
	s_cbranch_vccnz .LBB0_25
	s_andn2_b64 vcc, exec, s[10:11]
	s_cbranch_vccnz .LBB0_24
	s_barrier
	s_branch .LBB0_24
